# baseline (speedup 1.0000x reference)
; #define LAS __attribute__((address_space(3)))
; __global__ void __launch_bounds__(512, 2) fwd_megakernel(Params p) {
;   extern __shared__ __attribute__((aligned(16))) char lds[];
;   cg::grid_group grid = cg::this_grid();
;   unsigned* bar = (unsigned*)(p.ws + OFF_BAR);
;   volatile LAS unsigned* st = (volatile LAS unsigned*)(lds + LDS_BYTES);
;   {
;     const unsigned slot = (unsigned)__builtin_amdgcn_s_getreg((5 << 11) | 4) & 63u;
;     if ((threadIdx.x & 63) == 0) *(volatile __attribute__((address_space(3))) int*)(size_t)(WTBL_OFF + slot * 4) = (int)(threadIdx.x >> 6);
;     if (threadIdx.x == 0) { st[0] = 0u; st[1] = 0u; }
;     __syncthreads();
;   }
_Z14fwd_megakernel6Params:
	v_readfirstlane_b32 s100, v0
	s_nop 3
	s_bfe_u32 s100, s100, 0x40006
	s_cmp_ge_u32 s100, 4
	s_cbranch_scc0 .Lmy_prio_done
	s_setprio 1
.Lmy_prio_done:
	s_load_dword s14, s[0:1], 0xa8
	s_load_dwordx2 s[16:17], s[0:1], 0xa0
	s_mov_b32 s74, s2
	s_add_u32 s2, s0, 0xa0
	s_addc_u32 s3, s1, 0
	v_and_b32_e32 v1, 63, v0
	v_writelane_b32 v252, s2, 0
	s_getreg_b32 s4, hwreg(HW_REG_HW_ID, 0, 6)
	v_and_b32_e32 v6, 0x3ff, v0
	v_writelane_b32 v252, s3, 1
	v_cmp_eq_u32_e32 vcc, 0, v1
	s_and_saveexec_b64 s[2:3], vcc
	s_cbranch_execz .LBB0_2
	s_lshl_b32 s4, s4, 2
	s_and_b32 s4, s4, 0xfc
	s_add_i32 s4, s4, 0x20040
	v_lshrrev_b32_e32 v1, 6, v6
	v_mov_b32_e32 v2, s4
	ds_write_b32 v2, v1
